# v17 plus A-attention mask block: per 32-key sub-tile skip the mask when fully inside the window, fill -1e30 when fully outside
# speedup vs baseline: 1.0043x; 1.0017x over previous
; template <int MK> ...
;   f32x16 s0 = qk_tile(k0, L, q0, q1, q2, q3, init);
;   f32x16 s1 = qk_tile(k1, L, q0, q1, q2, q3, init);
;   if (MK == 2) {
; #pragma unroll
;     for (int v = 0; v < 16; ++v) { s0[v] += b0[(v & 3) + 8 * (v >> 2)]; s1[v] += b1[(v & 3) + 8 * (v >> 2)]; }
;   }
;   if (MK == 1 && kb1 != 0x7fffffff) {
;     const int lo = max(0, sq - 128), hi = min(2047, sq + 128);
;     const int L0 = lo - kb0 - 4 * h, H0 = hi - kb0 - 4 * h, L1 = lo - kb1 - 4 * h, H1 = hi - kb1 - 4 * h;
; #pragma unroll
;     for (int v = 0; v < 16; ++v) {
;       const int cv = (v & 3) + 8 * (v >> 2);
;       s0[v] = (cv >= L0 && cv <= H0) ? s0[v] : -1e30f;
;       s1[v] = (cv >= L1 && cv <= H1) ? s1[v] : -1e30f;
;     }
;   }
.LBB0_870:
	s_lshl_b32 s0, s33, 13
	s_add_i32 s33, s26, s0
	v_add_u32_e32 v0, s33, v139
	v_add_u32_e32 v6, s33, v140
	ds_read_b128 v[2:5], v0
	v_add_u32_e32 v7, s33, v141
	ds_read_b128 v[184:187], v6
	v_add_u32_e32 v8, s33, v142
	ds_read_b128 v[188:191], v7
	ds_read_b128 v[192:195], v8
	ds_read_b128 v[196:199], v0 offset:4096
	ds_read_b128 v[200:203], v6 offset:4096
	ds_read_b128 v[204:207], v7 offset:4096
	ds_read_b128 v[226:229], v8 offset:4096
	s_cmp_eq_u32 s69, 0x7fffffff
	s_waitcnt lgkmcnt(7)
	v_mfma_f32_32x32x16_bf16 v[80:95], v[2:5], v[96:99], v[48:63]
	s_waitcnt lgkmcnt(6)
	v_mfma_f32_32x32x16_bf16 v[80:95], v[184:187], v[100:103], v[80:95]
	s_waitcnt lgkmcnt(5)
	v_mfma_f32_32x32x16_bf16 v[80:95], v[188:191], v[104:107], v[80:95]
	s_waitcnt lgkmcnt(4)
	v_mfma_f32_32x32x16_bf16 v[80:95], v[192:195], v[108:111], v[80:95]
	s_waitcnt lgkmcnt(3)
	v_mfma_f32_32x32x16_bf16 v[64:79], v[196:199], v[96:99], v[48:63]
	s_waitcnt lgkmcnt(2)
	v_mfma_f32_32x32x16_bf16 v[64:79], v[200:203], v[100:103], v[64:79]
	s_waitcnt lgkmcnt(1)
	v_mfma_f32_32x32x16_bf16 v[64:79], v[204:207], v[104:107], v[64:79]
	s_waitcnt lgkmcnt(0)
	v_mfma_f32_32x32x16_bf16 v[64:79], v[226:229], v[108:111], v[64:79]
	s_nop 1
	s_cbranch_scc1 .LBB0_872
	v_add_u32_e32 v0, s72, v148
	v_sub_u32_e32 v2, v119, v0
	v_sub_u32_e32 v0, v170, v0
	v_add_u32_e32 v3, s69, v148
	v_sub_u32_e32 v4, v119, v3
	v_sub_u32_e32 v3, v170, v3
	s_sub_i32 s100, s22, 31
	s_cmp_lt_i32 s72, s100
	s_cbranch_scc1 .Lm0_mk0_inv
	s_cmp_lt_i32 s72, -31
	s_cbranch_scc1 .Lm0_mk0_inv
	s_cmp_gt_i32 s72, s21
	s_cbranch_scc1 .Lm0_mk0_inv
	s_cmp_gt_i32 s72, 0x7ff
	s_cbranch_scc1 .Lm0_mk0_inv
	s_cmp_lt_i32 s72, s23
	s_cbranch_scc1 .Lm0_mk0_part
	s_cmp_lt_i32 s72, 0
	s_cbranch_scc1 .Lm0_mk0_part
	s_add_i32 s100, s22, 0xe1
	s_cmp_gt_i32 s72, s100
	s_cbranch_scc1 .Lm0_mk0_part
	s_cmp_gt_i32 s72, 0x7e0
	s_cbranch_scc1 .Lm0_mk0_part
	s_branch .Lm0_mk1_begin
.Lm0_mk0_inv:
	v_mov_b32_e32 v80, v217
	v_mov_b32_e32 v81, v217
	v_mov_b32_e32 v82, v217
	v_mov_b32_e32 v83, v217
	v_mov_b32_e32 v84, v217
	v_mov_b32_e32 v85, v217
	v_mov_b32_e32 v86, v217
	v_mov_b32_e32 v87, v217
	v_mov_b32_e32 v88, v217
	v_mov_b32_e32 v89, v217
	v_mov_b32_e32 v90, v217
	v_mov_b32_e32 v91, v217
	v_mov_b32_e32 v92, v217
	v_mov_b32_e32 v93, v217
	v_mov_b32_e32 v94, v217
	v_mov_b32_e32 v95, v217
	s_branch .Lm0_mk1_begin
.Lm0_mk0_part:
	v_cmp_lt_i32_e32 vcc, 0, v2
	v_cmp_gt_i32_e64 s[0:1], 0, v0
	s_or_b64 vcc, vcc, s[0:1]
	v_cndmask_b32_e32 v80, v80, v217, vcc
	v_cmp_lt_i32_e32 vcc, 1, v2
	v_cmp_gt_i32_e64 s[0:1], 1, v0
	s_or_b64 vcc, vcc, s[0:1]
	v_cndmask_b32_e32 v81, v81, v217, vcc
	v_cmp_lt_i32_e32 vcc, 2, v2
	v_cmp_gt_i32_e64 s[0:1], 2, v0
	s_or_b64 vcc, vcc, s[0:1]
	v_cndmask_b32_e32 v82, v82, v217, vcc
	v_cmp_lt_i32_e32 vcc, 3, v2
	v_cmp_gt_i32_e64 s[0:1], 3, v0
	s_or_b64 vcc, vcc, s[0:1]
	v_cndmask_b32_e32 v83, v83, v217, vcc
	v_cmp_lt_i32_e32 vcc, 8, v2
	v_cmp_gt_i32_e64 s[0:1], 8, v0
	s_or_b64 vcc, vcc, s[0:1]
	v_cndmask_b32_e32 v84, v84, v217, vcc
	v_cmp_lt_i32_e32 vcc, 9, v2
	v_cmp_gt_i32_e64 s[0:1], 9, v0
	s_or_b64 vcc, vcc, s[0:1]
	v_cndmask_b32_e32 v85, v85, v217, vcc
	v_cmp_lt_i32_e32 vcc, 10, v2
	v_cmp_gt_i32_e64 s[0:1], 10, v0
	s_or_b64 vcc, vcc, s[0:1]
	v_cndmask_b32_e32 v86, v86, v217, vcc
	v_cmp_lt_i32_e32 vcc, 11, v2
	v_cmp_gt_i32_e64 s[0:1], 11, v0
	s_or_b64 vcc, vcc, s[0:1]
	v_cndmask_b32_e32 v87, v87, v217, vcc
	v_cmp_lt_i32_e32 vcc, 16, v2
	v_cmp_gt_i32_e64 s[0:1], 16, v0
	s_or_b64 vcc, vcc, s[0:1]
	v_cndmask_b32_e32 v88, v88, v217, vcc
	v_cmp_lt_i32_e32 vcc, 17, v2
	v_cmp_gt_i32_e64 s[0:1], 17, v0
	s_or_b64 vcc, vcc, s[0:1]
	v_cndmask_b32_e32 v89, v89, v217, vcc
	v_cmp_lt_i32_e32 vcc, 18, v2
	v_cmp_gt_i32_e64 s[0:1], 18, v0
	s_or_b64 vcc, vcc, s[0:1]
	v_cndmask_b32_e32 v90, v90, v217, vcc
	v_cmp_lt_i32_e32 vcc, 19, v2
	v_cmp_gt_i32_e64 s[0:1], 19, v0
	s_or_b64 vcc, vcc, s[0:1]
	v_cndmask_b32_e32 v91, v91, v217, vcc
	v_cmp_lt_i32_e32 vcc, 24, v2
	v_cmp_gt_i32_e64 s[0:1], 24, v0
	s_or_b64 vcc, vcc, s[0:1]
	v_cndmask_b32_e32 v92, v92, v217, vcc
	v_cmp_lt_i32_e32 vcc, 25, v2
	v_cmp_gt_i32_e64 s[0:1], 25, v0
	s_or_b64 vcc, vcc, s[0:1]
	v_cndmask_b32_e32 v93, v93, v217, vcc
	v_cmp_lt_i32_e32 vcc, 26, v2
	v_cmp_gt_i32_e64 s[0:1], 26, v0
	s_or_b64 vcc, vcc, s[0:1]
	v_cndmask_b32_e32 v94, v94, v217, vcc
	v_cmp_lt_i32_e32 vcc, 27, v2
	v_cmp_gt_i32_e64 s[0:1], 27, v0
	s_or_b64 vcc, vcc, s[0:1]
	v_cndmask_b32_e32 v95, v95, v217, vcc
; template <int MK> ...
;     ...
;   if (MK == 1 && kb1 != 0x7fffffff) {
;     const int lo = max(0, sq - 128), hi = min(2047, sq + 128);
;     const int L0 = lo - kb0 - 4 * h, H0 = hi - kb0 - 4 * h, L1 = lo - kb1 - 4 * h, H1 = hi - kb1 - 4 * h;
; #pragma unroll
;     for (int v = 0; v < 16; ++v) {
;       const int cv = (v & 3) + 8 * (v >> 2);
;       s0[v] = (cv >= L0 && cv <= H0) ? s0[v] : -1e30f;
;       s1[v] = (cv >= L1 && cv <= H1) ? s1[v] : -1e30f;
;     }
;   }
.Lm0_mk1_begin:
	s_sub_i32 s100, s22, 31
	s_cmp_lt_i32 s69, s100
	s_cbranch_scc1 .Lm0_mk1_inv
	s_cmp_lt_i32 s69, -31
	s_cbranch_scc1 .Lm0_mk1_inv
	s_cmp_gt_i32 s69, s21
	s_cbranch_scc1 .Lm0_mk1_inv
	s_cmp_gt_i32 s69, 0x7ff
	s_cbranch_scc1 .Lm0_mk1_inv
	s_cmp_lt_i32 s69, s23
	s_cbranch_scc1 .Lm0_mk1_part
	s_cmp_lt_i32 s69, 0
	s_cbranch_scc1 .Lm0_mk1_part
	s_add_i32 s100, s22, 0xe1
	s_cmp_gt_i32 s69, s100
	s_cbranch_scc1 .Lm0_mk1_part
	s_cmp_gt_i32 s69, 0x7e0
	s_cbranch_scc1 .Lm0_mk1_part
	s_branch .LBB0_872
.Lm0_mk1_inv:
	v_mov_b32_e32 v64, v217
	v_mov_b32_e32 v65, v217
	v_mov_b32_e32 v66, v217
	v_mov_b32_e32 v67, v217
	v_mov_b32_e32 v68, v217
	v_mov_b32_e32 v69, v217
	v_mov_b32_e32 v70, v217
	v_mov_b32_e32 v71, v217
	v_mov_b32_e32 v72, v217
	v_mov_b32_e32 v73, v217
	v_mov_b32_e32 v74, v217
	v_mov_b32_e32 v75, v217
	v_mov_b32_e32 v76, v217
	v_mov_b32_e32 v77, v217
	v_mov_b32_e32 v78, v217
	v_mov_b32_e32 v79, v217
	s_branch .LBB0_872
.Lm0_mk1_part:
	v_cmp_lt_i32_e32 vcc, 0, v4
	v_cmp_gt_i32_e64 s[0:1], 0, v3
	s_or_b64 vcc, vcc, s[0:1]
	v_cndmask_b32_e32 v64, v64, v217, vcc
	v_cmp_lt_i32_e32 vcc, 1, v4
	v_cmp_gt_i32_e64 s[0:1], 1, v3
	s_or_b64 vcc, vcc, s[0:1]
	v_cndmask_b32_e32 v65, v65, v217, vcc
	v_cmp_lt_i32_e32 vcc, 2, v4
	v_cmp_gt_i32_e64 s[0:1], 2, v3
	s_or_b64 vcc, vcc, s[0:1]
	v_cndmask_b32_e32 v66, v66, v217, vcc
	v_cmp_lt_i32_e32 vcc, 3, v4
	v_cmp_gt_i32_e64 s[0:1], 3, v3
	s_or_b64 vcc, vcc, s[0:1]
	v_cndmask_b32_e32 v67, v67, v217, vcc
	v_cmp_lt_i32_e32 vcc, 8, v4
	v_cmp_gt_i32_e64 s[0:1], 8, v3
	s_or_b64 vcc, vcc, s[0:1]
	v_cndmask_b32_e32 v68, v68, v217, vcc
	v_cmp_lt_i32_e32 vcc, 9, v4
	v_cmp_gt_i32_e64 s[0:1], 9, v3
	s_or_b64 vcc, vcc, s[0:1]
	v_cndmask_b32_e32 v69, v69, v217, vcc
	v_cmp_lt_i32_e32 vcc, 10, v4
	v_cmp_gt_i32_e64 s[0:1], 10, v3
	s_or_b64 vcc, vcc, s[0:1]
	v_cndmask_b32_e32 v70, v70, v217, vcc
	v_cmp_lt_i32_e32 vcc, 11, v4
	v_cmp_gt_i32_e64 s[0:1], 11, v3
	s_or_b64 vcc, vcc, s[0:1]
	v_cndmask_b32_e32 v71, v71, v217, vcc
	v_cmp_lt_i32_e32 vcc, 16, v4
	v_cmp_gt_i32_e64 s[0:1], 16, v3
	s_or_b64 vcc, vcc, s[0:1]
	v_cndmask_b32_e32 v72, v72, v217, vcc
	v_cmp_lt_i32_e32 vcc, 17, v4
	v_cmp_gt_i32_e64 s[0:1], 17, v3
	s_or_b64 vcc, vcc, s[0:1]
	v_cndmask_b32_e32 v73, v73, v217, vcc
	v_cmp_lt_i32_e32 vcc, 18, v4
	v_cmp_gt_i32_e64 s[0:1], 18, v3
	s_or_b64 vcc, vcc, s[0:1]
	v_cndmask_b32_e32 v74, v74, v217, vcc
	v_cmp_lt_i32_e32 vcc, 19, v4
	v_cmp_gt_i32_e64 s[0:1], 19, v3
	s_or_b64 vcc, vcc, s[0:1]
	v_cndmask_b32_e32 v75, v75, v217, vcc
	v_cmp_lt_i32_e32 vcc, 24, v4
	v_cmp_gt_i32_e64 s[0:1], 24, v3
	s_or_b64 vcc, vcc, s[0:1]
	v_cndmask_b32_e32 v76, v76, v217, vcc
	v_cmp_lt_i32_e32 vcc, 25, v4
	v_cmp_gt_i32_e64 s[0:1], 25, v3
	s_or_b64 vcc, vcc, s[0:1]
	v_cndmask_b32_e32 v77, v77, v217, vcc
	v_cmp_lt_i32_e32 vcc, 26, v4
	v_cmp_gt_i32_e64 s[0:1], 26, v3
	s_or_b64 vcc, vcc, s[0:1]
	v_cndmask_b32_e32 v78, v78, v217, vcc
	v_cmp_lt_i32_e32 vcc, 27, v4
	v_cmp_gt_i32_e64 s[0:1], 27, v3
	s_or_b64 vcc, vcc, s[0:1]
	v_cndmask_b32_e32 v79, v79, v217, vcc
